# previous plus half-workgroup alignment barriers around the epilogue kept only for the residual GEMM kind; other kinds stay staggered through the epilogue
# speedup vs baseline: 1.0148x; 1.0013x over previous
; #define PG8_BAR __builtin_amdgcn_s_barrier()
; template <class Epi, class Sched, bool ALIGN_EPI = false>
; __device__ __forceinline__ void gemm_phase(PG8_LAS unsigned char* lds, const Gemm g, const Sched& S, const Epi& E, int tid_in) {
;     ...
;         if constexpr (ALIGN_EPI) { if (wr == 0) PG8_BAR; }
;         E(acc, cur, wr, wc, fr, fq); S.done(cur);
.LBB0_271:
	s_cmp_eq_u32 s64, 2
	s_cbranch_scc0 .Lalign_a_skip
	s_barrier
.Lalign_a_skip:
	s_cmp_lt_i32 s64, 3
	s_mov_b64 s[58:59], -1
	s_cbranch_scc1 .LBB0_270

; #define PG8_WAIT_V(n) asm volatile("s_waitcnt vmcnt(" #n ")" ::: "memory")
; #define PG8_BAR __builtin_amdgcn_s_barrier()
; template <class Epi, class Sched, bool ALIGN_EPI = false>
; __device__ __forceinline__ void gemm_phase(PG8_LAS unsigned char* lds, const Gemm g, const Sched& S, const Epi& E, int tid_in) {
;     ...
;         if constexpr (ALIGN_EPI) { if (wr == 1) PG8_BAR; }
;     }
;     PG8_WAIT_V(0);
;     if constexpr (!ALIGN_EPI) { if (wr == 0) PG8_BAR; }
;     PG8_BAR;
.LBB0_379:
	s_andn2_b64 vcc, exec, s[12:13]
	s_cbranch_vccnz .LBB0_255
	s_cmp_eq_u32 s64, 2
	s_cbranch_scc0 .LBB0_255
	s_barrier
	s_branch .LBB0_255
.LBB0_381:
	s_waitcnt vmcnt(0)
	s_cmp_eq_u32 s64, 2
	s_cbranch_scc1 .Lfin_aligned
	s_and_b64 vcc, exec, s[14:15]
	s_cbranch_vccz .Lfin_aligned
	s_barrier
.Lfin_aligned:
	v_readlane_b32 s68, v254, 7
	v_readlane_b32 s69, v254, 8
	v_readlane_b32 s84, v255, 36
	v_readlane_b32 s70, v254, 9
	v_readlane_b32 s71, v254, 10
	v_readlane_b32 s63, v253, 56
	s_movk_i32 s66, 0x1000
	s_movk_i32 s77, 0x3c0
	s_movk_i32 s67, 0x1ff
	v_readlane_b32 s68, v253, 57
	s_movk_i32 s69, 0x100
	s_mov_b32 s72, 0x7ffff0
	s_movk_i32 s73, 0x4000
	s_movk_i32 s74, 0x7dff
	s_movk_i32 s75, 0x40e0
	s_movk_i32 s76, 0xc00
	s_movk_i32 s56, 0x90
	s_mov_b32 s78, 0x2aaaaaab
	s_mov_b64 s[82:83], s[94:95]
	v_readlane_b32 s79, v254, 6
	v_readlane_b32 s85, v255, 37
	v_readlane_b32 s86, v253, 55
	s_barrier
